# prologue: copy loop loads batched, bias dot product 32 rows per trip, serialized weight-prep tile copies prefetched
# speedup vs baseline: 1.0056x; 1.0056x over previous
.LBB0_3:
	s_mov_b32 s3, 0
	s_load_dwordx2 s[6:7], s[90:91], s3 offset:0x0
	s_waitcnt lgkmcnt(0)
	v_lshl_add_u64 v[34:35], s[12:13], 0, v[8:9]
	v_lshl_add_u64 v[30:31], s[6:7], 0, v[8:9]
	global_load_dwordx4 v[18:21], v[30:31], off
	global_load_dwordx4 v[68:71], v[30:31], off offset:1024
	global_load_dwordx4 v[72:75], v[30:31], off offset:2048
	global_load_dwordx4 v[76:79], v[30:31], off offset:3072
	v_readlane_b32 s6, v250, 0
	v_readlane_b32 s7, v250, 1
	s_waitcnt vmcnt(3)
	global_store_dwordx4 v[34:35], v[18:21], off
	v_lshl_add_u64 v[22:23], s[6:7], 0, v[6:7]
	v_add_co_u32_e64 v36, s[6:7], s0, v22
	v_cvt_pk_bf16_f32 v22, v18, v19
	s_nop 0
	v_addc_co_u32_e64 v37, s[6:7], 0, v23, s[6:7]
	v_cvt_pk_bf16_f32 v23, v20, v21
	global_store_dwordx2 v[36:37], v[22:23], off offset:1024
	s_waitcnt vmcnt(4)
	s_nop 1
	v_mov_b64_e32 v[22:23], v[68:69]
	v_mov_b64_e32 v[24:25], v[70:71]
	v_pk_mul_f32 v[18:19], v[18:19], v[18:19]
	v_pk_mul_f32 v[20:21], v[20:21], v[20:21]
	v_add_f32_e32 v18, v18, v19
	v_add_f32_e32 v18, v18, v20
	v_add_f32_e32 v38, v18, v21
	v_cmp_lt_i32_e64 s[6:7], v10, v3
	v_cvt_pk_bf16_f32 v26, v22, v23
	v_cvt_pk_bf16_f32 v27, v24, v25
	global_store_dwordx4 v[34:35], v[22:25], off offset:1024
	global_store_dwordx2 v[36:37], v[26:27], off offset:1536
	s_waitcnt vmcnt(5)
	s_nop 1
	v_mov_b64_e32 v[26:27], v[72:73]
	v_mov_b64_e32 v[28:29], v[74:75]
	v_pk_mul_f32 v[18:19], v[22:23], v[22:23]
	v_pk_mul_f32 v[20:21], v[24:25], v[24:25]
	v_add_f32_e32 v18, v18, v19
	v_add_f32_e32 v18, v18, v20
	v_add_f32_e32 v18, v18, v21
	v_add_f32_e32 v22, v38, v18
	v_cndmask_b32_e64 v17, v1, v10, s[6:7]
	v_lshlrev_b32_e32 v17, 2, v17
	v_cmp_lt_i32_e64 s[6:7], v11, v3
	v_cvt_pk_bf16_f32 v32, v26, v27
	v_cvt_pk_bf16_f32 v33, v28, v29
	global_store_dwordx4 v[34:35], v[26:29], off offset:2048
	global_store_dwordx2 v[36:37], v[32:33], off offset:2048
	s_waitcnt vmcnt(6)
	s_nop 1
	v_mov_b64_e32 v[30:31], v[76:77]
	v_mov_b64_e32 v[32:33], v[78:79]
	v_pk_mul_f32 v[18:19], v[26:27], v[26:27]
	v_pk_mul_f32 v[20:21], v[28:29], v[28:29]
	v_add_f32_e32 v18, v18, v19
	v_add_f32_e32 v18, v18, v20
	v_add_f32_e32 v18, v18, v21
	v_add_f32_e32 v22, v22, v18
	v_pk_mul_f32 v[18:19], v[30:31], v[30:31]
	v_pk_mul_f32 v[20:21], v[32:33], v[32:33]
	v_add_f32_e32 v18, v18, v19
	v_add_f32_e32 v18, v18, v20
	v_add_f32_e32 v18, v18, v21
	v_add_f32_e32 v18, v22, v18
	ds_bpermute_b32 v17, v17, v18
	v_cndmask_b32_e64 v19, v1, v11, s[6:7]
	v_lshlrev_b32_e32 v19, 2, v19
	v_cmp_lt_i32_e64 s[6:7], v12, v3
	v_cvt_pk_bf16_f32 v20, v30, v31
	s_waitcnt lgkmcnt(0)
	v_add_f32_e32 v17, v18, v17
	ds_bpermute_b32 v18, v19, v17
	v_cndmask_b32_e64 v19, v1, v12, s[6:7]
	v_lshlrev_b32_e32 v19, 2, v19
	v_cmp_lt_i32_e64 s[6:7], v13, v3
	v_cvt_pk_bf16_f32 v21, v32, v33
	s_waitcnt lgkmcnt(0)
	v_add_f32_e32 v17, v17, v18
	ds_bpermute_b32 v18, v19, v17
	v_cndmask_b32_e64 v19, v1, v13, s[6:7]
	v_lshlrev_b32_e32 v19, 2, v19
	v_cmp_lt_i32_e64 s[6:7], v14, v3
	global_store_dwordx4 v[34:35], v[30:33], off offset:3072
	s_waitcnt lgkmcnt(0)
	v_add_f32_e32 v17, v17, v18
	ds_bpermute_b32 v18, v19, v17
	v_cndmask_b32_e64 v19, v1, v14, s[6:7]
	v_lshlrev_b32_e32 v19, 2, v19
	v_cmp_lt_i32_e64 s[6:7], v15, v3
	global_store_dwordx2 v[36:37], v[20:21], off offset:2560
	s_waitcnt lgkmcnt(0)
	v_add_f32_e32 v17, v17, v18
	ds_bpermute_b32 v18, v19, v17
	v_cndmask_b32_e64 v19, v1, v15, s[6:7]
	s_waitcnt lgkmcnt(0)
	v_add_f32_e32 v17, v17, v18
	v_lshlrev_b32_e32 v18, 2, v19
	ds_bpermute_b32 v18, v18, v17
	s_and_saveexec_b64 s[6:7], vcc
	s_cbranch_execz .LBB0_2
	v_readlane_b32 s22, v250, 0
	v_readlane_b32 s23, v250, 1
	s_waitcnt lgkmcnt(0)
	v_add_f32_e32 v17, v17, v18
	v_cndmask_b32_e64 v17, 0, v17, s[4:5]
	v_lshl_add_u64 v[20:21], s[22:23], 0, v[4:5]
	global_store_dword v[20:21], v17, off
	s_branch .LBB0_2

.LBB0_22:
	v_mov_b32_e32 v14, v146
	s_nop 0
	v_readfirstlane_b32 s4, v14
	s_ashr_i32 s4, s4, 6
	s_add_i32 s33, s29, s4
	s_cmpk_gt_i32 s33, 0x21df
	s_cbranch_scc1 .LBB0_21
	s_mulk_i32 s4, 0x2100
	s_add_i32 s31, s4, 0
	v_and_b32_e32 v17, 63, v14
	s_cmpk_gt_i32 s33, 0x57f
	s_mov_b64 s[4:5], -1
	s_cbranch_scc0 .LBB0_129
	s_cmpk_gt_u32 s33, 0xaff
	s_cbranch_scc0 .LBB0_110
	s_cmpk_gt_u32 s33, 0x107f
	s_cbranch_scc0 .LBB0_107
	s_add_i32 s6, s33, 0xef80
	s_and_b32 s7, s6, 0xffff
	s_mulk_i32 s7, 0x75df
	s_lshr_b32 s7, s7, 23
	s_mul_i32 s11, s7, 0x116
	s_mov_b32 s4, 48
	s_sub_i32 s34, s6, s11
	s_lshl_b32 s6, s34, 5
	v_and_b32_e32 v10, 7, v14
	s_load_dwordx2 s[4:5], s[90:91], s4 offset:0x0
	s_and_b32 s35, s6, 0xffe0
	v_lshlrev_b32_e32 v12, 2, v10
	v_or_b32_e32 v2, s35, v12
	s_lshl_b32 s36, s7, 6
	v_cmp_gt_u32_e64 s[6:7], s17, v2
	v_mov_b32_e32 v4, v3
	v_mov_b32_e32 v5, v3
	v_cndmask_b32_e64 v2, 0, v2, s[6:7]
	v_lshlrev_b32_e32 v2, 2, v2
	s_waitcnt lgkmcnt(0)
	v_lshl_add_u64 v[8:9], s[4:5], 0, v[2:3]
	v_lshrrev_b32_e32 v11, 3, v17
	v_mov_b32_e32 v2, v3
	v_mov_b64_e32 v[6:7], v[4:5]
	s_mov_b32 s10, 40
	v_or_b32_e32 v13, s36, v11
	v_mov_b64_e32 v[4:5], v[2:3]
	s_and_saveexec_b64 s[4:5], s[6:7]
	s_cbranch_execz .LBB0_28
	v_mul_u32_u24_e32 v2, 0x22a4, v13
	v_lshlrev_b32_e32 v2, 2, v2
	v_lshl_add_u64 v[4:5], v[8:9], 0, v[2:3]
	v_mov_b32_e32 v104, 0x45480
	v_mov_b32_e32 v105, 0
	v_lshl_add_u64 v[106:107], v[4:5], 0, v[104:105]
	global_load_dwordx4 v[76:79], v[106:107], off
	v_lshl_add_u64 v[106:107], v[106:107], 0, v[104:105]
	global_load_dwordx4 v[80:83], v[106:107], off
	v_lshl_add_u64 v[106:107], v[106:107], 0, v[104:105]
	global_load_dwordx4 v[84:87], v[106:107], off
	v_lshl_add_u64 v[106:107], v[106:107], 0, v[104:105]
	global_load_dwordx4 v[88:91], v[106:107], off
	v_lshl_add_u64 v[106:107], v[106:107], 0, v[104:105]
	global_load_dwordx4 v[92:95], v[106:107], off
	v_lshl_add_u64 v[106:107], v[106:107], 0, v[104:105]
	global_load_dwordx4 v[96:99], v[106:107], off
	v_lshl_add_u64 v[106:107], v[106:107], 0, v[104:105]
	global_load_dwordx4 v[100:103], v[106:107], off
	global_load_dwordx4 v[4:7], v[4:5], off
.LBB0_28:
	s_or_b64 exec, exec, s[4:5]
	s_load_dwordx2 s[10:11], s[90:91], s10 offset:0x0
	s_waitcnt lgkmcnt(0)
	s_cmp_lg_u64 s[10:11], 0
	s_cselect_b64 s[12:13], -1, 0
	s_cmp_eq_u64 s[10:11], 0
	s_cbranch_scc1 .LBB0_30
	v_lshlrev_b32_e32 v2, 2, v13
	global_load_dword v108, v2, s[10:11] offset:128
	global_load_dword v2, v2, s[10:11]
	s_waitcnt vmcnt(0)
	v_pk_mul_f32 v[6:7], v[6:7], v[2:3] op_sel_hi:[1,0]
	v_pk_mul_f32 v[4:5], v[4:5], v[2:3] op_sel_hi:[1,0]
.LBB0_30:
	v_lshl_add_u32 v13, v12, 2, s31
	v_mad_u32_u24 v2, v11, s18, v13
	s_waitcnt vmcnt(0)
	ds_write2_b32 v2, v4, v5 offset1:1
	ds_write2_b32 v2, v6, v7 offset0:2 offset1:3
	v_mov_b32_e32 v4, v3
	v_mov_b32_e32 v5, v3
	v_mov_b32_e32 v2, v3
	v_mov_b64_e32 v[6:7], v[4:5]
	v_or_b32_e32 v19, 8, v11
	v_mov_b64_e32 v[4:5], v[2:3]
	s_and_saveexec_b64 s[4:5], s[6:7]
	s_cbranch_execz .LBB0_32
	v_or_b32_e32 v2, s36, v19
	v_mul_u32_u24_e32 v2, 0x22a4, v2
	v_lshlrev_b32_e32 v2, 2, v2
	v_lshl_add_u64 v[4:5], v[8:9], 0, v[2:3]
	s_waitcnt vmcnt(0)
	v_mov_b64_e32 v[4:5], v[76:77]
	v_mov_b64_e32 v[6:7], v[78:79]

.LBB0_34:
	v_mul_u32_u24_e32 v2, 0x84, v11
	v_add_u32_e32 v13, v2, v13
	v_add_u32_e32 v2, 0x420, v13
	s_waitcnt vmcnt(0)
	ds_write2_b32 v2, v4, v5 offset1:1
	v_add_u32_e32 v2, 0x428, v13
	v_mov_b32_e32 v4, v3
	v_mov_b32_e32 v5, v3
	ds_write2_b32 v2, v6, v7 offset1:1
	v_mov_b32_e32 v2, v3
	v_mov_b64_e32 v[6:7], v[4:5]
	v_or_b32_e32 v18, 16, v11
	v_mov_b64_e32 v[4:5], v[2:3]
	s_and_saveexec_b64 s[12:13], s[6:7]
	s_cbranch_execz .LBB0_36
	v_or_b32_e32 v2, s36, v18
	v_mul_u32_u24_e32 v2, 0x22a4, v2
	v_lshlrev_b32_e32 v2, 2, v2
	v_lshl_add_u64 v[4:5], v[8:9], 0, v[2:3]
	v_mov_b64_e32 v[4:5], v[80:81]
	v_mov_b64_e32 v[6:7], v[82:83]

.LBB0_38:
	v_add_u32_e32 v2, 0x840, v13
	s_waitcnt vmcnt(0)
	ds_write2_b32 v2, v4, v5 offset1:1
	v_add_u32_e32 v2, 0x848, v13
	v_mov_b32_e32 v4, v3
	v_mov_b32_e32 v5, v3
	ds_write2_b32 v2, v6, v7 offset1:1
	v_mov_b32_e32 v2, v3
	v_mov_b64_e32 v[6:7], v[4:5]
	v_or_b32_e32 v15, 24, v11
	v_mov_b64_e32 v[4:5], v[2:3]
	s_and_saveexec_b64 s[12:13], s[6:7]
	s_cbranch_execz .LBB0_40
	v_or_b32_e32 v2, s36, v15
	v_mul_u32_u24_e32 v2, 0x22a4, v2
	v_lshlrev_b32_e32 v2, 2, v2
	v_lshl_add_u64 v[4:5], v[8:9], 0, v[2:3]
	v_mov_b64_e32 v[4:5], v[84:85]
	v_mov_b64_e32 v[6:7], v[86:87]

.LBB0_42:
	v_add_u32_e32 v2, 0xc60, v13
	s_waitcnt vmcnt(0)
	ds_write2_b32 v2, v4, v5 offset1:1
	v_add_u32_e32 v2, 0xc68, v13
	v_mov_b32_e32 v4, v3
	v_mov_b32_e32 v5, v3
	ds_write2_b32 v2, v6, v7 offset1:1
	v_mov_b32_e32 v2, v3
	v_mov_b64_e32 v[6:7], v[4:5]
	v_mov_b64_e32 v[4:5], v[2:3]
	s_and_saveexec_b64 s[12:13], s[6:7]
	s_cbranch_execz .LBB0_44
	v_or3_b32 v2, v11, s36, 32
	v_mul_u32_u24_e32 v2, 0x22a4, v2
	v_lshlrev_b32_e32 v2, 2, v2
	v_lshl_add_u64 v[4:5], v[8:9], 0, v[2:3]
	v_mov_b64_e32 v[4:5], v[88:89]
	v_mov_b64_e32 v[6:7], v[90:91]

.LBB0_46:
	v_add_u32_e32 v2, 0x1080, v13
	s_waitcnt vmcnt(0)
	ds_write2_b32 v2, v4, v5 offset1:1
	v_add_u32_e32 v2, 0x1088, v13
	v_mov_b32_e32 v4, v3
	v_mov_b32_e32 v5, v3
	ds_write2_b32 v2, v6, v7 offset1:1
	v_mov_b32_e32 v2, v3
	v_mov_b64_e32 v[6:7], v[4:5]
	v_mov_b64_e32 v[4:5], v[2:3]
	s_and_saveexec_b64 s[12:13], s[6:7]
	s_cbranch_execz .LBB0_48
	v_or3_b32 v2, v11, s36, 40
	v_mul_u32_u24_e32 v2, 0x22a4, v2
	v_lshlrev_b32_e32 v2, 2, v2
	v_lshl_add_u64 v[4:5], v[8:9], 0, v[2:3]
	v_mov_b64_e32 v[4:5], v[92:93]
	v_mov_b64_e32 v[6:7], v[94:95]

.LBB0_50:
	v_add_u32_e32 v2, 0x14a0, v13
	s_waitcnt vmcnt(0)
	ds_write2_b32 v2, v4, v5 offset1:1
	v_add_u32_e32 v2, 0x14a8, v13
	v_mov_b32_e32 v4, v3
	v_mov_b32_e32 v5, v3
	ds_write2_b32 v2, v6, v7 offset1:1
	v_mov_b32_e32 v2, v3
	v_mov_b64_e32 v[6:7], v[4:5]
	v_mov_b64_e32 v[4:5], v[2:3]
	s_and_saveexec_b64 s[12:13], s[6:7]
	s_cbranch_execz .LBB0_52
	v_or3_b32 v2, v11, s36, 48
	v_mul_u32_u24_e32 v2, 0x22a4, v2
	v_lshlrev_b32_e32 v2, 2, v2
	v_lshl_add_u64 v[4:5], v[8:9], 0, v[2:3]
	v_mov_b64_e32 v[4:5], v[96:97]
	v_mov_b64_e32 v[6:7], v[98:99]

.LBB0_54:
	v_add_u32_e32 v2, 0x18c0, v13
	s_waitcnt vmcnt(0)
	ds_write2_b32 v2, v4, v5 offset1:1
	v_add_u32_e32 v2, 0x18c8, v13
	v_mov_b32_e32 v4, v3
	v_mov_b32_e32 v5, v3
	ds_write2_b32 v2, v6, v7 offset1:1
	v_mov_b32_e32 v2, v3
	v_mov_b64_e32 v[6:7], v[4:5]
	v_mov_b64_e32 v[4:5], v[2:3]
	s_and_saveexec_b64 s[12:13], s[6:7]
	s_cbranch_execz .LBB0_56
	v_or3_b32 v2, v11, s36, 56
	v_mul_u32_u24_e32 v2, 0x22a4, v2
	v_lshlrev_b32_e32 v2, 2, v2
	v_lshl_add_u64 v[4:5], v[8:9], 0, v[2:3]
	v_mov_b64_e32 v[4:5], v[100:101]
	v_mov_b64_e32 v[6:7], v[102:103]

.LBB0_110:
	s_andn2_b64 vcc, exec, s[4:5]
	s_cbranch_vccnz .LBB0_128
	s_add_i32 s7, s33, 0xfa80
	s_and_b32 s10, s7, 0xffff
	s_mul_i32 s10, s10, 0xba2f
	s_mov_b32 s4, 24
	s_lshr_b32 s11, s10, 16
	s_lshr_b32 s10, s10, 22
	s_mulk_i32 s10, 0x58
	s_load_dwordx2 s[4:5], s[90:91], s4 offset:0x0
	s_sub_i32 s7, s7, s10
	s_lshl_b32 s7, s7, 5
	s_waitcnt lgkmcnt(0)
	v_and_b32_e32 v18, 7, v14
	s_and_b32 s12, s7, 0xffe0
	v_lshlrev_b32_e32 v20, 2, v18
	s_and_b32 s13, s11, 0xffc0
	v_or_b32_e32 v2, s12, v20
	v_lshrrev_b32_e32 v15, 3, v17
	v_lshlrev_b32_e32 v2, 2, v2
	v_or_b32_e32 v4, s13, v15
	v_lshl_add_u64 v[12:13], s[4:5], 0, v[2:3]
	v_mul_u32_u24_e32 v2, 0xb00, v4
	v_lshlrev_b32_e32 v2, 2, v2
	s_mov_b32 s6, 8
	v_lshl_add_u64 v[6:7], v[12:13], 0, v[2:3]
	v_mov_b32_e32 v104, 0x16000
	v_mov_b32_e32 v105, 0
	v_lshl_add_u64 v[106:107], v[6:7], 0, v[104:105]
	global_load_dwordx4 v[76:79], v[106:107], off
	v_lshl_add_u64 v[106:107], v[106:107], 0, v[104:105]
	global_load_dwordx4 v[80:83], v[106:107], off
	v_lshl_add_u64 v[106:107], v[106:107], 0, v[104:105]
	global_load_dwordx4 v[84:87], v[106:107], off
	v_lshl_add_u64 v[106:107], v[106:107], 0, v[104:105]
	global_load_dwordx4 v[88:91], v[106:107], off
	v_lshl_add_u64 v[106:107], v[106:107], 0, v[104:105]
	global_load_dwordx4 v[92:95], v[106:107], off
	v_lshl_add_u64 v[106:107], v[106:107], 0, v[104:105]
	global_load_dwordx4 v[96:99], v[106:107], off
	v_lshl_add_u64 v[106:107], v[106:107], 0, v[104:105]
	global_load_dwordx4 v[100:103], v[106:107], off
	global_load_dwordx4 v[8:11], v[6:7], off
	s_load_dwordx2 s[6:7], s[90:91], s6 offset:0x0
	s_waitcnt lgkmcnt(0)
	s_cmp_lg_u64 s[6:7], 0
	s_cselect_b64 s[10:11], -1, 0
	s_cmp_eq_u64 s[6:7], 0
	s_cbranch_scc1 .LBB0_113
	v_lshlrev_b32_e32 v2, 2, v4
	global_load_dword v108, v2, s[6:7] offset:128
	global_load_dword v2, v2, s[6:7]
	s_waitcnt vmcnt(0)
	v_pk_mul_f32 v[10:11], v[10:11], v[2:3] op_sel_hi:[1,0]
	v_pk_mul_f32 v[8:9], v[8:9], v[2:3] op_sel_hi:[1,0]
.LBB0_113:
	v_or_b32_e32 v19, 8, v15
	v_or_b32_e32 v2, s13, v19
	v_mul_u32_u24_e32 v2, 0xb00, v2
	v_lshlrev_b32_e32 v2, 2, v2
	v_lshl_add_u64 v[4:5], v[12:13], 0, v[2:3]
	s_waitcnt vmcnt(0)
	v_mov_b64_e32 v[4:5], v[76:77]
	v_mov_b64_e32 v[6:7], v[78:79]
	v_lshl_add_u32 v21, v20, 2, s31
	v_mad_u32_u24 v2, v15, s18, v21
	s_waitcnt vmcnt(1)
	ds_write2_b32 v2, v8, v9 offset1:1
	ds_write2_b32 v2, v10, v11 offset0:2 offset1:3
	v_cndmask_b32_e64 v2, 0, 1, s[10:11]
	v_cmp_ne_u32_e64 s[4:5], 1, v2
	s_andn2_b64 vcc, exec, s[10:11]
	v_add_lshl_u32 v22, v15, s13, 2
	s_cbranch_vccnz .LBB0_115
	global_load_dword v2, v22, s[6:7] offset:32
	s_waitcnt vmcnt(0)
	v_pk_mul_f32 v[6:7], v[6:7], v[2:3] op_sel_hi:[1,0]
	v_pk_mul_f32 v[4:5], v[4:5], v[2:3] op_sel_hi:[1,0]
.LBB0_115:
	v_or_b32_e32 v20, 16, v15
	v_or_b32_e32 v2, s13, v20
	v_mul_u32_u24_e32 v2, 0xb00, v2
	v_lshlrev_b32_e32 v2, 2, v2
	v_lshl_add_u64 v[8:9], v[12:13], 0, v[2:3]
	v_mov_b64_e32 v[8:9], v[80:81]
	v_mov_b64_e32 v[10:11], v[82:83]
	v_mul_u32_u24_e32 v2, 0x84, v15
	v_add_u32_e32 v23, v2, v21
	v_add_u32_e32 v2, 0x420, v23
	s_waitcnt vmcnt(1)
	ds_write2_b32 v2, v4, v5 offset1:1
	v_add_u32_e32 v2, 0x428, v23
	s_and_b64 vcc, exec, s[4:5]
	ds_write2_b32 v2, v6, v7 offset1:1
	s_cbranch_vccnz .LBB0_117
	global_load_dword v2, v22, s[6:7] offset:64
	s_waitcnt vmcnt(0)
	v_pk_mul_f32 v[10:11], v[10:11], v[2:3] op_sel_hi:[1,0]
	v_pk_mul_f32 v[8:9], v[8:9], v[2:3] op_sel_hi:[1,0]
.LBB0_117:
	v_or_b32_e32 v21, 24, v15
	v_or_b32_e32 v2, s13, v21
	v_mul_u32_u24_e32 v2, 0xb00, v2
	v_lshlrev_b32_e32 v2, 2, v2
	v_lshl_add_u64 v[4:5], v[12:13], 0, v[2:3]
	v_mov_b64_e32 v[4:5], v[84:85]
	v_mov_b64_e32 v[6:7], v[86:87]
	v_add_u32_e32 v2, 0x840, v23
	s_waitcnt vmcnt(1)
	ds_write2_b32 v2, v8, v9 offset1:1
	v_add_u32_e32 v2, 0x848, v23
	s_and_b64 vcc, exec, s[4:5]
	ds_write2_b32 v2, v10, v11 offset1:1
	s_cbranch_vccnz .LBB0_119
	global_load_dword v2, v22, s[6:7] offset:96
	s_waitcnt vmcnt(0)
	v_pk_mul_f32 v[6:7], v[6:7], v[2:3] op_sel_hi:[1,0]
	v_pk_mul_f32 v[4:5], v[4:5], v[2:3] op_sel_hi:[1,0]
.LBB0_119:
	v_or3_b32 v2, v15, s13, 32
	v_mul_u32_u24_e32 v2, 0xb00, v2
	v_lshlrev_b32_e32 v2, 2, v2
	v_lshl_add_u64 v[8:9], v[12:13], 0, v[2:3]
	v_mov_b64_e32 v[8:9], v[88:89]
	v_mov_b64_e32 v[10:11], v[90:91]
	v_add_u32_e32 v2, 0xc60, v23
	s_waitcnt vmcnt(1)
	ds_write2_b32 v2, v4, v5 offset1:1
	v_add_u32_e32 v2, 0xc68, v23
	s_and_b64 vcc, exec, s[4:5]
	ds_write2_b32 v2, v6, v7 offset1:1
	s_cbranch_vccnz .LBB0_121
	global_load_dword v2, v22, s[6:7] offset:128
	s_waitcnt vmcnt(0)
	v_pk_mul_f32 v[10:11], v[10:11], v[2:3] op_sel_hi:[1,0]
	v_pk_mul_f32 v[8:9], v[8:9], v[2:3] op_sel_hi:[1,0]
.LBB0_121:
	v_or3_b32 v2, v15, s13, 40
	v_mul_u32_u24_e32 v2, 0xb00, v2
	v_lshlrev_b32_e32 v2, 2, v2
	v_lshl_add_u64 v[4:5], v[12:13], 0, v[2:3]
	v_mov_b64_e32 v[4:5], v[92:93]
	v_mov_b64_e32 v[6:7], v[94:95]
	v_add_u32_e32 v2, 0x1080, v23
	s_waitcnt vmcnt(1)
	ds_write2_b32 v2, v8, v9 offset1:1
	v_add_u32_e32 v2, 0x1088, v23
	s_and_b64 vcc, exec, s[4:5]
	ds_write2_b32 v2, v10, v11 offset1:1
	s_cbranch_vccnz .LBB0_123
	global_load_dword v2, v22, s[6:7] offset:160
	s_waitcnt vmcnt(0)
	v_pk_mul_f32 v[6:7], v[6:7], v[2:3] op_sel_hi:[1,0]
	v_pk_mul_f32 v[4:5], v[4:5], v[2:3] op_sel_hi:[1,0]
.LBB0_123:
	v_or3_b32 v2, v15, s13, 48
	v_mul_u32_u24_e32 v2, 0xb00, v2
	v_lshlrev_b32_e32 v2, 2, v2
	v_lshl_add_u64 v[8:9], v[12:13], 0, v[2:3]
	v_mov_b64_e32 v[8:9], v[96:97]
	v_mov_b64_e32 v[10:11], v[98:99]
	v_add_u32_e32 v2, 0x14a0, v23
	s_waitcnt vmcnt(1)
	ds_write2_b32 v2, v4, v5 offset1:1
	v_add_u32_e32 v2, 0x14a8, v23
	s_and_b64 vcc, exec, s[4:5]
	ds_write2_b32 v2, v6, v7 offset1:1
	s_cbranch_vccnz .LBB0_125
	global_load_dword v2, v22, s[6:7] offset:192
	s_waitcnt vmcnt(0)
	v_pk_mul_f32 v[10:11], v[10:11], v[2:3] op_sel_hi:[1,0]
	v_pk_mul_f32 v[8:9], v[8:9], v[2:3] op_sel_hi:[1,0]
.LBB0_125:
	v_or3_b32 v2, v15, s13, 56
	v_mul_u32_u24_e32 v2, 0xb00, v2
	v_lshlrev_b32_e32 v2, 2, v2
	v_lshl_add_u64 v[4:5], v[12:13], 0, v[2:3]
	v_mov_b64_e32 v[4:5], v[100:101]
	v_mov_b64_e32 v[6:7], v[102:103]
	v_add_u32_e32 v2, 0x18c0, v23
	s_waitcnt vmcnt(1)
	ds_write2_b32 v2, v8, v9 offset1:1
	v_add_u32_e32 v2, 0x18c8, v23
	s_and_b64 vcc, exec, s[4:5]
	ds_write2_b32 v2, v10, v11 offset1:1
	s_cbranch_vccnz .LBB0_127
	global_load_dword v2, v22, s[6:7] offset:224
	s_waitcnt vmcnt(0)
	v_pk_mul_f32 v[6:7], v[6:7], v[2:3] op_sel_hi:[1,0]
	v_pk_mul_f32 v[4:5], v[4:5], v[2:3] op_sel_hi:[1,0]

.LBB0_129:
	s_andn2_b64 vcc, exec, s[4:5]
	s_cbranch_vccnz .LBB0_21
	s_mul_hi_i32 s6, s33, 0x2e8ba2e9
	s_mov_b32 s4, 16
	s_lshr_b32 s10, s6, 31
	s_ashr_i32 s6, s6, 4
	s_add_i32 s6, s6, s10
	s_load_dwordx2 s[4:5], s[90:91], s4 offset:0x0
	s_mul_i32 s10, s6, 0x58
	s_sub_i32 s10, s33, s10
	v_and_b32_e32 v2, 7, v14
	s_lshl_b32 s33, s10, 5
	v_lshlrev_b32_e32 v13, 2, v2
	v_or_b32_e32 v4, s33, v13
	s_lshl_b32 s6, s6, 6
	v_ashrrev_i32_e32 v5, 31, v4
	v_lshrrev_b32_e32 v12, 3, v17
	s_waitcnt lgkmcnt(0)
	v_lshl_add_u64 v[14:15], v[4:5], 2, s[4:5]
	v_or_b32_e32 v4, s6, v12
	s_mov_b32 s7, 8
	v_mad_i64_i32 v[6:7], s[4:5], v4, s25, v[14:15]
	v_mov_b32_e32 v104, 0x16000
	v_mov_b32_e32 v105, 0
	v_lshl_add_u64 v[106:107], v[6:7], 0, v[104:105]
	global_load_dwordx4 v[76:79], v[106:107], off
	v_lshl_add_u64 v[106:107], v[106:107], 0, v[104:105]
	global_load_dwordx4 v[80:83], v[106:107], off
	v_lshl_add_u64 v[106:107], v[106:107], 0, v[104:105]
	global_load_dwordx4 v[84:87], v[106:107], off
	v_lshl_add_u64 v[106:107], v[106:107], 0, v[104:105]
	global_load_dwordx4 v[88:91], v[106:107], off
	v_lshl_add_u64 v[106:107], v[106:107], 0, v[104:105]
	global_load_dwordx4 v[92:95], v[106:107], off
	v_lshl_add_u64 v[106:107], v[106:107], 0, v[104:105]
	global_load_dwordx4 v[96:99], v[106:107], off
	v_lshl_add_u64 v[106:107], v[106:107], 0, v[104:105]
	global_load_dwordx4 v[100:103], v[106:107], off
	global_load_dwordx4 v[8:11], v[6:7], off
	s_load_dwordx2 s[10:11], s[90:91], s7 offset:0x0
	s_waitcnt lgkmcnt(0)
	s_cmp_lg_u64 s[10:11], 0
	s_cselect_b64 s[12:13], -1, 0
	s_cmp_eq_u64 s[10:11], 0
	s_cbranch_scc1 .LBB0_132
	v_ashrrev_i32_e32 v5, 31, v4
	v_lshl_add_u64 v[4:5], v[4:5], 2, s[10:11]
	global_load_dword v108, v[4:5], off offset:128
	global_load_dword v4, v[4:5], off
	s_waitcnt vmcnt(0)
	v_pk_mul_f32 v[10:11], v[10:11], v[4:5] op_sel_hi:[1,0]
	v_pk_mul_f32 v[8:9], v[8:9], v[4:5] op_sel_hi:[1,0]
.LBB0_132:
	v_or_b32_e32 v18, 8, v12
	v_or_b32_e32 v4, s6, v18
	v_mad_i64_i32 v[4:5], s[4:5], v4, s25, v[14:15]
	s_waitcnt vmcnt(0)
	v_mov_b64_e32 v[4:5], v[76:77]
	v_mov_b64_e32 v[6:7], v[78:79]
	v_lshl_add_u32 v20, v13, 2, s31
	v_mad_u32_u24 v13, v12, s18, v20
	s_waitcnt vmcnt(1)
	ds_write2_b32 v13, v8, v9 offset1:1
	v_cndmask_b32_e64 v8, 0, 1, s[12:13]
	v_cmp_ne_u32_e64 s[4:5], 1, v8
	s_andn2_b64 vcc, exec, s[12:13]
	ds_write2_b32 v13, v10, v11 offset0:2 offset1:3
	s_cbranch_vccnz .LBB0_134
	s_ashr_i32 s7, s6, 31
	v_mov_b32_e32 v13, v3
	v_lshl_add_u64 v[8:9], s[6:7], 0, v[12:13]
	v_lshl_add_u64 v[8:9], v[8:9], 2, s[10:11]
	global_load_dword v8, v[8:9], off offset:32
	s_waitcnt vmcnt(0)
	v_pk_mul_f32 v[6:7], v[6:7], v[8:9] op_sel_hi:[1,0]
	v_pk_mul_f32 v[4:5], v[4:5], v[8:9] op_sel_hi:[1,0]
.LBB0_134:
	v_or_b32_e32 v19, 16, v12
	v_or_b32_e32 v8, s6, v19
	v_mad_i64_i32 v[8:9], s[34:35], v8, s25, v[14:15]
	v_mov_b64_e32 v[8:9], v[80:81]
	v_mov_b64_e32 v[10:11], v[82:83]
	v_mul_u32_u24_e32 v13, 0x84, v12
	v_add_u32_e32 v21, v13, v20
	v_add_u32_e32 v13, 0x420, v21
	s_waitcnt vmcnt(1)
	ds_write2_b32 v13, v4, v5 offset1:1
	v_add_u32_e32 v4, 0x428, v21
	s_and_b64 vcc, exec, s[4:5]
	ds_write2_b32 v4, v6, v7 offset1:1
	s_cbranch_vccnz .LBB0_136
	s_ashr_i32 s7, s6, 31
	v_mov_b32_e32 v13, v3
	v_lshl_add_u64 v[4:5], s[6:7], 0, v[12:13]
	v_lshl_add_u64 v[4:5], v[4:5], 2, s[10:11]
	global_load_dword v4, v[4:5], off offset:64
	s_waitcnt vmcnt(0)
	v_pk_mul_f32 v[10:11], v[10:11], v[4:5] op_sel_hi:[1,0]
	v_pk_mul_f32 v[8:9], v[8:9], v[4:5] op_sel_hi:[1,0]
.LBB0_136:
	v_or_b32_e32 v20, 24, v12
	v_or_b32_e32 v4, s6, v20
	v_mad_i64_i32 v[4:5], s[34:35], v4, s25, v[14:15]
	v_mov_b64_e32 v[4:5], v[84:85]
	v_mov_b64_e32 v[6:7], v[86:87]
	v_add_u32_e32 v13, 0x840, v21
	s_waitcnt vmcnt(1)
	ds_write2_b32 v13, v8, v9 offset1:1
	v_add_u32_e32 v8, 0x848, v21
	s_and_b64 vcc, exec, s[4:5]
	ds_write2_b32 v8, v10, v11 offset1:1
	s_cbranch_vccnz .LBB0_138
	s_ashr_i32 s7, s6, 31
	v_mov_b32_e32 v13, v3
	v_lshl_add_u64 v[8:9], s[6:7], 0, v[12:13]
	v_lshl_add_u64 v[8:9], v[8:9], 2, s[10:11]
	global_load_dword v8, v[8:9], off offset:96
	s_waitcnt vmcnt(0)
	v_pk_mul_f32 v[6:7], v[6:7], v[8:9] op_sel_hi:[1,0]
	v_pk_mul_f32 v[4:5], v[4:5], v[8:9] op_sel_hi:[1,0]
.LBB0_138:
	v_or3_b32 v8, v12, s6, 32
	v_mad_i64_i32 v[8:9], s[34:35], v8, s25, v[14:15]
	v_mov_b64_e32 v[8:9], v[88:89]
	v_mov_b64_e32 v[10:11], v[90:91]
	v_add_u32_e32 v13, 0xc60, v21
	s_waitcnt vmcnt(1)
	ds_write2_b32 v13, v4, v5 offset1:1
	v_add_u32_e32 v4, 0xc68, v21
	s_and_b64 vcc, exec, s[4:5]
	ds_write2_b32 v4, v6, v7 offset1:1
	s_cbranch_vccnz .LBB0_140
	s_ashr_i32 s7, s6, 31
	v_mov_b32_e32 v13, v3
	v_lshl_add_u64 v[4:5], s[6:7], 0, v[12:13]
	v_lshl_add_u64 v[4:5], v[4:5], 2, s[10:11]
	global_load_dword v4, v[4:5], off offset:128
	s_waitcnt vmcnt(0)
	v_pk_mul_f32 v[10:11], v[10:11], v[4:5] op_sel_hi:[1,0]
	v_pk_mul_f32 v[8:9], v[8:9], v[4:5] op_sel_hi:[1,0]
.LBB0_140:
	v_or3_b32 v4, v12, s6, 40
	v_mad_i64_i32 v[4:5], s[34:35], v4, s25, v[14:15]
	v_mov_b64_e32 v[4:5], v[92:93]
	v_mov_b64_e32 v[6:7], v[94:95]
	v_add_u32_e32 v13, 0x1080, v21
	s_waitcnt vmcnt(1)
	ds_write2_b32 v13, v8, v9 offset1:1
	v_add_u32_e32 v8, 0x1088, v21
	s_and_b64 vcc, exec, s[4:5]
	ds_write2_b32 v8, v10, v11 offset1:1
	s_cbranch_vccnz .LBB0_142
	s_ashr_i32 s7, s6, 31
	v_mov_b32_e32 v13, v3
	v_lshl_add_u64 v[8:9], s[6:7], 0, v[12:13]
	v_lshl_add_u64 v[8:9], v[8:9], 2, s[10:11]
	global_load_dword v8, v[8:9], off offset:160
	s_waitcnt vmcnt(0)
	v_pk_mul_f32 v[6:7], v[6:7], v[8:9] op_sel_hi:[1,0]
	v_pk_mul_f32 v[4:5], v[4:5], v[8:9] op_sel_hi:[1,0]
.LBB0_142:
	v_or3_b32 v8, v12, s6, 48
	v_mad_i64_i32 v[8:9], s[34:35], v8, s25, v[14:15]
	v_mov_b64_e32 v[8:9], v[96:97]
	v_mov_b64_e32 v[10:11], v[98:99]
	v_add_u32_e32 v13, 0x14a0, v21
	s_waitcnt vmcnt(1)
	ds_write2_b32 v13, v4, v5 offset1:1
	v_add_u32_e32 v4, 0x14a8, v21
	s_and_b64 vcc, exec, s[4:5]
	ds_write2_b32 v4, v6, v7 offset1:1
	s_cbranch_vccnz .LBB0_144
	s_ashr_i32 s7, s6, 31
	v_mov_b32_e32 v13, v3
	v_lshl_add_u64 v[4:5], s[6:7], 0, v[12:13]
	v_lshl_add_u64 v[4:5], v[4:5], 2, s[10:11]
	global_load_dword v4, v[4:5], off offset:192
	s_waitcnt vmcnt(0)
	v_pk_mul_f32 v[10:11], v[10:11], v[4:5] op_sel_hi:[1,0]
	v_pk_mul_f32 v[8:9], v[8:9], v[4:5] op_sel_hi:[1,0]
.LBB0_144:
	v_or3_b32 v4, v12, s6, 56
	v_mad_i64_i32 v[4:5], s[4:5], v4, s25, v[14:15]
	v_mov_b64_e32 v[4:5], v[100:101]
	v_mov_b64_e32 v[6:7], v[102:103]
	v_add_u32_e32 v13, 0x18c0, v21
	s_waitcnt vmcnt(1)
	ds_write2_b32 v13, v8, v9 offset1:1
	v_add_u32_e32 v8, 0x18c8, v21
	s_and_b64 vcc, exec, s[12:13]
	ds_write2_b32 v8, v10, v11 offset1:1
	s_cbranch_vccz .LBB0_146
	s_ashr_i32 s7, s6, 31
	v_mov_b32_e32 v13, v3
	v_lshl_add_u64 v[8:9], s[6:7], 0, v[12:13]
	v_lshl_add_u64 v[8:9], v[8:9], 2, s[10:11]
	global_load_dword v8, v[8:9], off offset:224
	s_waitcnt vmcnt(0)
	v_pk_mul_f32 v[10:11], v[6:7], v[8:9] op_sel_hi:[1,0]
	v_pk_mul_f32 v[8:9], v[4:5], v[8:9] op_sel_hi:[1,0]
	s_cbranch_execnz .LBB0_20
	s_branch .LBB0_19

.LBB0_165:
	s_add_u32 s44, s42, s20
	v_add_co_u32_e32 v6, vcc, s34, v2
	s_addc_u32 s45, s43, s21
	s_nop 0
	v_addc_co_u32_e32 v7, vcc, -1, v3, vcc
	v_lshl_add_u64 v[14:15], v[2:3], 0, s[12:13]
	v_lshl_add_u64 v[18:19], v[14:15], 0, s[12:13]
	v_lshl_add_u64 v[20:21], v[18:19], 0, s[12:13]
	global_load_dwordx4 v[72:75], v9, s[44:45] offset:16
	global_load_dwordx4 v[68:71], v9, s[44:45]
	global_load_dwordx4 v[80:83], v9, s[44:45] offset:48
	global_load_dwordx4 v[76:79], v9, s[44:45] offset:32
	global_load_dwordx4 v[88:91], v9, s[44:45] offset:80
	global_load_dwordx4 v[84:87], v9, s[44:45] offset:64
	global_load_dwordx4 v[96:99], v9, s[44:45] offset:112
	global_load_dwordx4 v[92:95], v9, s[44:45] offset:96
	global_load_dword v100, v[6:7], off offset:-3072
	global_load_dword v101, v[6:7], off offset:-2048
	global_load_dword v102, v[6:7], off offset:-1024
	global_load_dword v103, v[2:3], off offset:-4096
	global_load_dword v104, v[2:3], off offset:-3072
	global_load_dword v105, v[2:3], off offset:-2048
	global_load_dword v106, v[2:3], off offset:-1024
	global_load_dword v107, v[2:3], off
	global_load_dword v108, v[2:3], off offset:1024
	global_load_dword v109, v[2:3], off offset:2048
	global_load_dword v110, v[2:3], off offset:3072
	global_load_dword v111, v[14:15], off offset:-4096
	global_load_dword v112, v[14:15], off offset:-3072
	global_load_dword v113, v[14:15], off offset:-2048
	global_load_dword v114, v[14:15], off offset:-1024
	global_load_dword v26, v[14:15], off
	global_load_dword v27, v[14:15], off offset:1024
	global_load_dword v28, v[14:15], off offset:2048
	global_load_dword v29, v[14:15], off offset:3072
	global_load_dword v30, v[18:19], off offset:-4096
	global_load_dword v31, v[18:19], off offset:-3072
	global_load_dword v32, v[18:19], off offset:-2048
	global_load_dword v33, v[18:19], off offset:-1024
	global_load_dword v34, v[18:19], off
	global_load_dword v35, v[18:19], off offset:1024
	global_load_dword v36, v[18:19], off offset:2048
	global_load_dword v37, v[18:19], off offset:3072
	global_load_dword v38, v[20:21], off offset:-4096
	global_load_dword v39, v[20:21], off offset:-3072
	global_load_dword v8, v[20:21], off offset:-2048
	global_load_dword v10, v[20:21], off offset:-1024
	global_load_dword v11, v[20:21], off
	s_add_u32 s20, s20, 0x80
	s_addc_u32 s21, s21, 0
	v_lshl_add_u64 v[2:3], v[20:21], 0, s[12:13]
	s_cmpk_eq_i32 s20, 0x400
	s_waitcnt vmcnt(31)
	v_fmac_f32_e32 v5, v68, v100
	s_waitcnt vmcnt(30)
	v_fmac_f32_e32 v5, v69, v101
	s_waitcnt vmcnt(29)
	v_fmac_f32_e32 v5, v70, v102
	s_waitcnt vmcnt(28)
	v_fmac_f32_e32 v5, v71, v103
	s_waitcnt vmcnt(27)
	v_fmac_f32_e32 v5, v72, v104
	s_waitcnt vmcnt(26)
	v_fmac_f32_e32 v5, v73, v105
	s_waitcnt vmcnt(25)
	v_fmac_f32_e32 v5, v74, v106
	s_waitcnt vmcnt(24)
	v_fmac_f32_e32 v5, v75, v107
	s_waitcnt vmcnt(23)
	v_fmac_f32_e32 v5, v76, v108
	s_waitcnt vmcnt(22)
	v_fmac_f32_e32 v5, v77, v109
	s_waitcnt vmcnt(21)
	v_fmac_f32_e32 v5, v78, v110
	s_waitcnt vmcnt(20)
	v_fmac_f32_e32 v5, v79, v111
	s_waitcnt vmcnt(19)
	v_fmac_f32_e32 v5, v80, v112
	s_waitcnt vmcnt(18)
	v_fmac_f32_e32 v5, v81, v113
	s_waitcnt vmcnt(17)
	v_fmac_f32_e32 v5, v82, v114
	s_waitcnt vmcnt(16)
	v_fmac_f32_e32 v5, v83, v26
	s_waitcnt vmcnt(15)
	v_fmac_f32_e32 v5, v84, v27
	s_waitcnt vmcnt(14)
	v_fmac_f32_e32 v5, v85, v28
	s_waitcnt vmcnt(13)
	v_fmac_f32_e32 v5, v86, v29
	s_waitcnt vmcnt(12)
	v_fmac_f32_e32 v5, v87, v30
	s_waitcnt vmcnt(11)
	v_fmac_f32_e32 v5, v88, v31
	s_waitcnt vmcnt(10)
	v_fmac_f32_e32 v5, v89, v32
	s_waitcnt vmcnt(9)
	v_fmac_f32_e32 v5, v90, v33
	s_waitcnt vmcnt(8)
	v_fmac_f32_e32 v5, v91, v34
	s_waitcnt vmcnt(7)
	v_fmac_f32_e32 v5, v92, v35
	s_waitcnt vmcnt(6)
	v_fmac_f32_e32 v5, v93, v36
	s_waitcnt vmcnt(5)
	v_fmac_f32_e32 v5, v94, v37
	s_waitcnt vmcnt(4)
	v_fmac_f32_e32 v5, v95, v38
	s_waitcnt vmcnt(3)
	v_fmac_f32_e32 v5, v96, v39
	s_waitcnt vmcnt(2)
	v_fmac_f32_e32 v5, v97, v8
	s_waitcnt vmcnt(1)
	v_fmac_f32_e32 v5, v98, v10
	s_waitcnt vmcnt(0)
	v_fmac_f32_e32 v5, v99, v11
	s_cbranch_scc0 .LBB0_165
	s_lshl_b32 s20, s41, 5
	s_and_b32 s20, s20, 0xffffff00
	v_or_b32_e32 v8, s20, v4
	v_lshl_add_u64 v[2:3], v[8:9], 2, s[4:5]
	global_store_dword v[2:3], v5, off
